# ffn1 SwiGLU epilogue rewritten by hand: row-ssq loads hoisted (1 wait instead of 8), 8 sigmoid chains interleaved without hazard nops
# speedup vs baseline: 1.0871x; 1.0058x over previous
; __device__ __forceinline__ unsigned cvt_pk_bf16(float lo, float hi) { unsigned r; asm volatile("v_cvt_pk_bf16_f32 %0, %1, %2" : "=v"(r) : "v"(lo), "v"(hi)); return r; }
; __device__ __forceinline__ float sigmoidf_(float x) { return 1.0f / (1.0f + __builtin_amdgcn_exp2f(-1.4426950408889634f * x)); }
;     __device__ __forceinline__ void operator()(const f32x4 (&acc)[2][2][4][2], const Unit& u, int wr, int wc, int fr, int fq) const {
;     ...
;         const size_t rowb = (size_t)u.pm * BM + wr * 64 + fr; const int col0 = u.pn * HALF + wc * 32 + 8 * fq;
;         const float* bwp = bw + (size_t)(u.pm >> 4) * 5632 + u.pn * BM + wc * 32 + 8 * fq;
;         const f32x4 bg0 = *(const f32x4*)bwp, bg1 = *(const f32x4*)(bwp + 4), bu0 = *(const f32x4*)(bwp + HALF), bu1 = *(const f32x4*)(bwp + HALF + 4);
; #pragma unroll
;         for (int ai = 0; ai < 2; ++ai)
; #pragma unroll
;             for (int m = 0; m < 4; ++m) { const size_t row = rowb + ai * HALF + m * 16; const float r = __builtin_amdgcn_rsqf(ssq2[row] * (1.0f / 1024.0f) + RMS_EPS);
;                 f32x4 g0 = acc[ai][0][m][0] * r + bg0, g1 = acc[ai][0][m][1] * r + bg1; const f32x4 u0 = acc[ai][1][m][0] * r + bu0, u1 = acc[ai][1][m][1] * r + bu1;
; #pragma unroll
;                 for (int i = 0; i < 4; ++i) { g0[i] = g0[i] * sigmoidf_(g0[i]) * u0[i]; g1[i] = g1[i] * sigmoidf_(g1[i]) * u1[i]; }
;                 u32x4 w; w.x = cvt_pk_bf16(g0[0], g0[1]); w.y = cvt_pk_bf16(g0[2], g0[3]); w.z = cvt_pk_bf16(g1[0], g1[1]); w.w = cvt_pk_bf16(g1[2], g1[3]);
;                 *(u32x4*)(O + row * 2816 + col0) = w; }
.LBB0_33:
	s_ashr_i32 s35, s34, 31
	v_mov_b32_e32 v26, v221
	s_lshl_b64 s[38:39], s[34:35], 8
	s_add_u32 s15, s38, s55
	s_addc_u32 s13, s39, s59
	v_and_or_b32 v160, v26, 15, s15
	s_lshl_b32 s15, s63, 7
	v_lshrrev_b32_e32 v26, 1, v26
	s_or_b32 s15, s15, s56
	v_and_b32_e32 v26, 24, v26
	v_or_b32_e32 v162, s15, v26
	s_ashr_i32 s15, s34, 4
	s_mul_hi_i32 s34, s15, 0x5800
	s_mulk_i32 s15, 0x5800
	s_add_u32 s15, s53, s15
	s_addc_u32 s38, s54, s34
	s_lshl_b32 s34, s63, 8
	s_ashr_i32 s35, s34, 31
	s_lshl_b64 s[34:35], s[34:35], 2
	s_add_u32 s15, s15, s34
	v_mov_b32_e32 v161, s13
	s_addc_u32 s35, s38, s35
	s_add_u32 s34, s15, s62
	v_lshlrev_b64 v[158:159], 2, v[160:161]
	s_addc_u32 s35, s35, 0
	v_lshlrev_b32_e32 v30, 2, v26
	v_lshl_add_u64 v[156:157], s[8:9], 0, v[158:159]
	global_load_dwordx4 v[50:53], v30, s[34:35] offset:16
	global_load_dwordx4 v[54:57], v30, s[34:35]
	global_load_dwordx4 v[26:29], v30, s[34:35] offset:528
	s_nop 0
	global_load_dwordx4 v[30:33], v30, s[34:35] offset:512
	s_movk_i32 s15, 0x1600
	global_load_dword v161, v[156:157], off
	v_ashrrev_i32_e32 v163, 31, v162
	global_load_dword v233, v[156:157], off offset:0
	global_load_dword v234, v[156:157], off offset:64
	global_load_dword v235, v[156:157], off offset:128
	global_load_dword v236, v[156:157], off offset:192
	global_load_dword v237, v[156:157], off offset:512
	global_load_dword v238, v[156:157], off offset:576
	global_load_dword v239, v[156:157], off offset:640
	global_load_dword v240, v[156:157], off offset:704
	v_mul_u32_u24_e32 v252, 0x1600, v160
	v_lshl_add_u32 v252, v162, 1, v252
	s_waitcnt vmcnt(0)
	v_fmamk_f32 v242, v233, 0x3a800000, v231
	v_rsq_f32_e32 v242, v242
	s_nop 0
	v_pk_fma_f32 v[142:143], v[142:143], v[242:243], v[54:55] op_sel_hi:[1,0,1]
	v_pk_fma_f32 v[144:145], v[144:145], v[242:243], v[56:57] op_sel_hi:[1,0,1]
	v_pk_fma_f32 v[138:139], v[138:139], v[242:243], v[50:51] op_sel_hi:[1,0,1]
	v_pk_fma_f32 v[140:141], v[140:141], v[242:243], v[52:53] op_sel_hi:[1,0,1]
	v_pk_fma_f32 v[134:135], v[134:135], v[242:243], v[30:31] op_sel_hi:[1,0,1]
	v_pk_fma_f32 v[136:137], v[136:137], v[242:243], v[32:33] op_sel_hi:[1,0,1]
	v_pk_fma_f32 v[130:131], v[130:131], v[242:243], v[26:27] op_sel_hi:[1,0,1]
	v_pk_fma_f32 v[132:133], v[132:133], v[242:243], v[28:29] op_sel_hi:[1,0,1]
	v_mul_f32_e32 v244, 0xbfb8aa3b, v142
	v_mul_f32_e32 v245, 0xbfb8aa3b, v143
	v_mul_f32_e32 v246, 0xbfb8aa3b, v144
	v_mul_f32_e32 v247, 0xbfb8aa3b, v145
	v_mul_f32_e32 v248, 0xbfb8aa3b, v138
	v_mul_f32_e32 v249, 0xbfb8aa3b, v139
	v_mul_f32_e32 v250, 0xbfb8aa3b, v140
	v_mul_f32_e32 v251, 0xbfb8aa3b, v141
	v_exp_f32_e32 v244, v244
	v_exp_f32_e32 v245, v245
	v_exp_f32_e32 v246, v246
	v_exp_f32_e32 v247, v247
	v_exp_f32_e32 v248, v248
	v_exp_f32_e32 v249, v249
	v_exp_f32_e32 v250, v250
	v_exp_f32_e32 v251, v251
	v_add_f32_e32 v244, 1.0, v244
	v_add_f32_e32 v245, 1.0, v245
	v_add_f32_e32 v246, 1.0, v246
	v_add_f32_e32 v247, 1.0, v247
	v_add_f32_e32 v248, 1.0, v248
	v_add_f32_e32 v249, 1.0, v249
	v_add_f32_e32 v250, 1.0, v250
	v_add_f32_e32 v251, 1.0, v251
	v_rcp_f32_e32 v244, v244
	v_rcp_f32_e32 v245, v245
	v_rcp_f32_e32 v246, v246
	v_rcp_f32_e32 v247, v247
	v_rcp_f32_e32 v248, v248
	v_rcp_f32_e32 v249, v249
	v_rcp_f32_e32 v250, v250
	v_rcp_f32_e32 v251, v251
	v_mul_f32_e32 v244, v142, v244
	v_mul_f32_e32 v245, v143, v245
	v_mul_f32_e32 v246, v144, v246
	v_mul_f32_e32 v247, v145, v247
	v_mul_f32_e32 v248, v138, v248
	v_mul_f32_e32 v249, v139, v249
	v_mul_f32_e32 v250, v140, v250
	v_mul_f32_e32 v251, v141, v251
	v_mul_f32_e32 v244, v134, v244
	v_mul_f32_e32 v245, v135, v245
	v_mul_f32_e32 v246, v136, v246
	v_mul_f32_e32 v247, v137, v247
	v_mul_f32_e32 v248, v130, v248
	v_mul_f32_e32 v249, v131, v249
	v_mul_f32_e32 v250, v132, v250
	v_mul_f32_e32 v251, v133, v251
	v_cvt_pk_bf16_f32 v156, v244, v245
	v_cvt_pk_bf16_f32 v157, v246, v247
	v_cvt_pk_bf16_f32 v158, v248, v249
	v_cvt_pk_bf16_f32 v159, v250, v251
	global_store_dwordx4 v252, v[156:159], s[6:7]
	v_add_u32_e32 v252, 0x16000, v252
	v_fmamk_f32 v242, v234, 0x3a800000, v231
	v_rsq_f32_e32 v242, v242
	s_nop 0
	v_pk_fma_f32 v[126:127], v[126:127], v[242:243], v[54:55] op_sel_hi:[1,0,1]
	v_pk_fma_f32 v[128:129], v[128:129], v[242:243], v[56:57] op_sel_hi:[1,0,1]
	v_pk_fma_f32 v[122:123], v[122:123], v[242:243], v[50:51] op_sel_hi:[1,0,1]
	v_pk_fma_f32 v[124:125], v[124:125], v[242:243], v[52:53] op_sel_hi:[1,0,1]
	v_pk_fma_f32 v[118:119], v[118:119], v[242:243], v[30:31] op_sel_hi:[1,0,1]
	v_pk_fma_f32 v[120:121], v[120:121], v[242:243], v[32:33] op_sel_hi:[1,0,1]
	v_pk_fma_f32 v[114:115], v[114:115], v[242:243], v[26:27] op_sel_hi:[1,0,1]
	v_pk_fma_f32 v[116:117], v[116:117], v[242:243], v[28:29] op_sel_hi:[1,0,1]
	v_mul_f32_e32 v244, 0xbfb8aa3b, v126
	v_mul_f32_e32 v245, 0xbfb8aa3b, v127
	v_mul_f32_e32 v246, 0xbfb8aa3b, v128
	v_mul_f32_e32 v247, 0xbfb8aa3b, v129
	v_mul_f32_e32 v248, 0xbfb8aa3b, v122
	v_mul_f32_e32 v249, 0xbfb8aa3b, v123
	v_mul_f32_e32 v250, 0xbfb8aa3b, v124
	v_mul_f32_e32 v251, 0xbfb8aa3b, v125
	v_exp_f32_e32 v244, v244
	v_exp_f32_e32 v245, v245
	v_exp_f32_e32 v246, v246
	v_exp_f32_e32 v247, v247
	v_exp_f32_e32 v248, v248
	v_exp_f32_e32 v249, v249
	v_exp_f32_e32 v250, v250
	v_exp_f32_e32 v251, v251
	v_add_f32_e32 v244, 1.0, v244
	v_add_f32_e32 v245, 1.0, v245
	v_add_f32_e32 v246, 1.0, v246
	v_add_f32_e32 v247, 1.0, v247
	v_add_f32_e32 v248, 1.0, v248
	v_add_f32_e32 v249, 1.0, v249
	v_add_f32_e32 v250, 1.0, v250
	v_add_f32_e32 v251, 1.0, v251
	v_rcp_f32_e32 v244, v244
	v_rcp_f32_e32 v245, v245
	v_rcp_f32_e32 v246, v246
	v_rcp_f32_e32 v247, v247
	v_rcp_f32_e32 v248, v248
	v_rcp_f32_e32 v249, v249
	v_rcp_f32_e32 v250, v250
; __device__ __forceinline__ unsigned cvt_pk_bf16(float lo, float hi) { unsigned r; asm volatile("v_cvt_pk_bf16_f32 %0, %1, %2" : "=v"(r) : "v"(lo), "v"(hi)); return r; }
; __device__ __forceinline__ float sigmoidf_(float x) { return 1.0f / (1.0f + __builtin_amdgcn_exp2f(-1.4426950408889634f * x)); }
;     __device__ __forceinline__ void operator()(const f32x4 (&acc)[2][2][4][2], const Unit& u, int wr, int wc, int fr, int fq) const {
;     ...
; #pragma unroll
;             for (int m = 0; m < 4; ++m) { const size_t row = rowb + ai * HALF + m * 16; const float r = __builtin_amdgcn_rsqf(ssq2[row] * (1.0f / 1024.0f) + RMS_EPS);
;                 f32x4 g0 = acc[ai][0][m][0] * r + bg0, g1 = acc[ai][0][m][1] * r + bg1; const f32x4 u0 = acc[ai][1][m][0] * r + bu0, u1 = acc[ai][1][m][1] * r + bu1;
; #pragma unroll
;                 for (int i = 0; i < 4; ++i) { g0[i] = g0[i] * sigmoidf_(g0[i]) * u0[i]; g1[i] = g1[i] * sigmoidf_(g1[i]) * u1[i]; }
;                 u32x4 w; w.x = cvt_pk_bf16(g0[0], g0[1]); w.y = cvt_pk_bf16(g0[2], g0[3]); w.z = cvt_pk_bf16(g1[0], g1[1]); w.w = cvt_pk_bf16(g1[2], g1[3]);
;                 *(u32x4*)(O + row * 2816 + col0) = w; }
	v_rcp_f32_e32 v251, v251
	v_mul_f32_e32 v244, v126, v244
	v_mul_f32_e32 v245, v127, v245
	v_mul_f32_e32 v246, v128, v246
	v_mul_f32_e32 v247, v129, v247
	v_mul_f32_e32 v248, v122, v248
	v_mul_f32_e32 v249, v123, v249
	v_mul_f32_e32 v250, v124, v250
	v_mul_f32_e32 v251, v125, v251
	v_mul_f32_e32 v244, v118, v244
	v_mul_f32_e32 v245, v119, v245
	v_mul_f32_e32 v246, v120, v246
	v_mul_f32_e32 v247, v121, v247
	v_mul_f32_e32 v248, v114, v248
	v_mul_f32_e32 v249, v115, v249
	v_mul_f32_e32 v250, v116, v250
	v_mul_f32_e32 v251, v117, v251
	v_cvt_pk_bf16_f32 v156, v244, v245
	v_cvt_pk_bf16_f32 v157, v246, v247
	v_cvt_pk_bf16_f32 v158, v248, v249
	v_cvt_pk_bf16_f32 v159, v250, v251
	global_store_dwordx4 v252, v[156:159], s[6:7]
	v_add_u32_e32 v252, 0x16000, v252
	v_fmamk_f32 v242, v235, 0x3a800000, v231
	v_rsq_f32_e32 v242, v242
	s_nop 0
	v_pk_fma_f32 v[110:111], v[110:111], v[242:243], v[54:55] op_sel_hi:[1,0,1]
	v_pk_fma_f32 v[112:113], v[112:113], v[242:243], v[56:57] op_sel_hi:[1,0,1]
	v_pk_fma_f32 v[106:107], v[106:107], v[242:243], v[50:51] op_sel_hi:[1,0,1]
	v_pk_fma_f32 v[108:109], v[108:109], v[242:243], v[52:53] op_sel_hi:[1,0,1]
	v_pk_fma_f32 v[102:103], v[102:103], v[242:243], v[30:31] op_sel_hi:[1,0,1]
	v_pk_fma_f32 v[104:105], v[104:105], v[242:243], v[32:33] op_sel_hi:[1,0,1]
	v_pk_fma_f32 v[98:99], v[98:99], v[242:243], v[26:27] op_sel_hi:[1,0,1]
	v_pk_fma_f32 v[100:101], v[100:101], v[242:243], v[28:29] op_sel_hi:[1,0,1]
	v_mul_f32_e32 v244, 0xbfb8aa3b, v110
	v_mul_f32_e32 v245, 0xbfb8aa3b, v111
	v_mul_f32_e32 v246, 0xbfb8aa3b, v112
	v_mul_f32_e32 v247, 0xbfb8aa3b, v113
	v_mul_f32_e32 v248, 0xbfb8aa3b, v106
	v_mul_f32_e32 v249, 0xbfb8aa3b, v107
	v_mul_f32_e32 v250, 0xbfb8aa3b, v108
	v_mul_f32_e32 v251, 0xbfb8aa3b, v109
	v_exp_f32_e32 v244, v244
	v_exp_f32_e32 v245, v245
	v_exp_f32_e32 v246, v246
	v_exp_f32_e32 v247, v247
	v_exp_f32_e32 v248, v248
	v_exp_f32_e32 v249, v249
	v_exp_f32_e32 v250, v250
	v_exp_f32_e32 v251, v251
	v_add_f32_e32 v244, 1.0, v244
	v_add_f32_e32 v245, 1.0, v245
	v_add_f32_e32 v246, 1.0, v246
	v_add_f32_e32 v247, 1.0, v247
	v_add_f32_e32 v248, 1.0, v248
	v_add_f32_e32 v249, 1.0, v249
	v_add_f32_e32 v250, 1.0, v250
	v_add_f32_e32 v251, 1.0, v251
	v_rcp_f32_e32 v244, v244
	v_rcp_f32_e32 v245, v245
	v_rcp_f32_e32 v246, v246
	v_rcp_f32_e32 v247, v247
	v_rcp_f32_e32 v248, v248
	v_rcp_f32_e32 v249, v249
	v_rcp_f32_e32 v250, v250
	v_rcp_f32_e32 v251, v251
	v_mul_f32_e32 v244, v110, v244
	v_mul_f32_e32 v245, v111, v245
	v_mul_f32_e32 v246, v112, v246
	v_mul_f32_e32 v247, v113, v247
	v_mul_f32_e32 v248, v106, v248
	v_mul_f32_e32 v249, v107, v249
	v_mul_f32_e32 v250, v108, v250
	v_mul_f32_e32 v251, v109, v251
	v_mul_f32_e32 v244, v102, v244
	v_mul_f32_e32 v245, v103, v245
	v_mul_f32_e32 v246, v104, v246
	v_mul_f32_e32 v247, v105, v247
	v_mul_f32_e32 v248, v98, v248
	v_mul_f32_e32 v249, v99, v249
	v_mul_f32_e32 v250, v100, v250
	v_mul_f32_e32 v251, v101, v251
	v_cvt_pk_bf16_f32 v156, v244, v245
	v_cvt_pk_bf16_f32 v157, v246, v247
	v_cvt_pk_bf16_f32 v158, v248, v249
	v_cvt_pk_bf16_f32 v159, v250, v251
	global_store_dwordx4 v252, v[156:159], s[6:7]
	v_add_u32_e32 v252, 0x16000, v252
	v_fmamk_f32 v242, v236, 0x3a800000, v231
	v_rsq_f32_e32 v242, v242
	s_nop 0
	v_pk_fma_f32 v[94:95], v[94:95], v[242:243], v[54:55] op_sel_hi:[1,0,1]
	v_pk_fma_f32 v[96:97], v[96:97], v[242:243], v[56:57] op_sel_hi:[1,0,1]
	v_pk_fma_f32 v[90:91], v[90:91], v[242:243], v[50:51] op_sel_hi:[1,0,1]
	v_pk_fma_f32 v[92:93], v[92:93], v[242:243], v[52:53] op_sel_hi:[1,0,1]
	v_pk_fma_f32 v[86:87], v[86:87], v[242:243], v[30:31] op_sel_hi:[1,0,1]
	v_pk_fma_f32 v[88:89], v[88:89], v[242:243], v[32:33] op_sel_hi:[1,0,1]
	v_pk_fma_f32 v[82:83], v[82:83], v[242:243], v[26:27] op_sel_hi:[1,0,1]
	v_pk_fma_f32 v[84:85], v[84:85], v[242:243], v[28:29] op_sel_hi:[1,0,1]
	v_mul_f32_e32 v244, 0xbfb8aa3b, v94
	v_mul_f32_e32 v245, 0xbfb8aa3b, v95
	v_mul_f32_e32 v246, 0xbfb8aa3b, v96
	v_mul_f32_e32 v247, 0xbfb8aa3b, v97
	v_mul_f32_e32 v248, 0xbfb8aa3b, v90
	v_mul_f32_e32 v249, 0xbfb8aa3b, v91
	v_mul_f32_e32 v250, 0xbfb8aa3b, v92
	v_mul_f32_e32 v251, 0xbfb8aa3b, v93
	v_exp_f32_e32 v244, v244
	v_exp_f32_e32 v245, v245
	v_exp_f32_e32 v246, v246
	v_exp_f32_e32 v247, v247
	v_exp_f32_e32 v248, v248
	v_exp_f32_e32 v249, v249
	v_exp_f32_e32 v250, v250
	v_exp_f32_e32 v251, v251
	v_add_f32_e32 v244, 1.0, v244
	v_add_f32_e32 v245, 1.0, v245
	v_add_f32_e32 v246, 1.0, v246
	v_add_f32_e32 v247, 1.0, v247
	v_add_f32_e32 v248, 1.0, v248
	v_add_f32_e32 v249, 1.0, v249
	v_add_f32_e32 v250, 1.0, v250
	v_add_f32_e32 v251, 1.0, v251
	v_rcp_f32_e32 v244, v244
	v_rcp_f32_e32 v245, v245
	v_rcp_f32_e32 v246, v246
	v_rcp_f32_e32 v247, v247
	v_rcp_f32_e32 v248, v248
	v_rcp_f32_e32 v249, v249
	v_rcp_f32_e32 v250, v250
	v_rcp_f32_e32 v251, v251
	v_mul_f32_e32 v244, v94, v244
	v_mul_f32_e32 v245, v95, v245
	v_mul_f32_e32 v246, v96, v246
	v_mul_f32_e32 v247, v97, v247
	v_mul_f32_e32 v248, v90, v248
	v_mul_f32_e32 v249, v91, v249
	v_mul_f32_e32 v250, v92, v250
	v_mul_f32_e32 v251, v93, v251
	v_mul_f32_e32 v244, v86, v244
	v_mul_f32_e32 v245, v87, v245
	v_mul_f32_e32 v246, v88, v246
	v_mul_f32_e32 v247, v89, v247
	v_mul_f32_e32 v248, v82, v248
	v_mul_f32_e32 v249, v83, v249
	v_mul_f32_e32 v250, v84, v250
	v_mul_f32_e32 v251, v85, v251
	v_cvt_pk_bf16_f32 v156, v244, v245
	v_cvt_pk_bf16_f32 v157, v246, v247
	v_cvt_pk_bf16_f32 v158, v248, v249
	v_cvt_pk_bf16_f32 v159, v250, v251
	global_store_dwordx4 v252, v[156:159], s[6:7]
	v_add_u32_e32 v252, 0x6e000, v252
	v_fmamk_f32 v242, v237, 0x3a800000, v231
	v_rsq_f32_e32 v242, v242
	s_nop 0
	v_pk_fma_f32 v[78:79], v[78:79], v[242:243], v[54:55] op_sel_hi:[1,0,1]
; __device__ __forceinline__ unsigned cvt_pk_bf16(float lo, float hi) { unsigned r; asm volatile("v_cvt_pk_bf16_f32 %0, %1, %2" : "=v"(r) : "v"(lo), "v"(hi)); return r; }
; __device__ __forceinline__ float sigmoidf_(float x) { return 1.0f / (1.0f + __builtin_amdgcn_exp2f(-1.4426950408889634f * x)); }
;     __device__ __forceinline__ void operator()(const f32x4 (&acc)[2][2][4][2], const Unit& u, int wr, int wc, int fr, int fq) const {
;     ...
;             for (int m = 0; m < 4; ++m) { const size_t row = rowb + ai * HALF + m * 16; const float r = __builtin_amdgcn_rsqf(ssq2[row] * (1.0f / 1024.0f) + RMS_EPS);
;                 f32x4 g0 = acc[ai][0][m][0] * r + bg0, g1 = acc[ai][0][m][1] * r + bg1; const f32x4 u0 = acc[ai][1][m][0] * r + bu0, u1 = acc[ai][1][m][1] * r + bu1;
; #pragma unroll
;                 for (int i = 0; i < 4; ++i) { g0[i] = g0[i] * sigmoidf_(g0[i]) * u0[i]; g1[i] = g1[i] * sigmoidf_(g1[i]) * u1[i]; }
;                 u32x4 w; w.x = cvt_pk_bf16(g0[0], g0[1]); w.y = cvt_pk_bf16(g0[2], g0[3]); w.z = cvt_pk_bf16(g1[0], g1[1]); w.w = cvt_pk_bf16(g1[2], g1[3]);
;                 *(u32x4*)(O + row * 2816 + col0) = w; }
	v_pk_fma_f32 v[80:81], v[80:81], v[242:243], v[56:57] op_sel_hi:[1,0,1]
	v_pk_fma_f32 v[74:75], v[74:75], v[242:243], v[50:51] op_sel_hi:[1,0,1]
	v_pk_fma_f32 v[76:77], v[76:77], v[242:243], v[52:53] op_sel_hi:[1,0,1]
	v_pk_fma_f32 v[70:71], v[70:71], v[242:243], v[30:31] op_sel_hi:[1,0,1]
	v_pk_fma_f32 v[72:73], v[72:73], v[242:243], v[32:33] op_sel_hi:[1,0,1]
	v_pk_fma_f32 v[62:63], v[62:63], v[242:243], v[26:27] op_sel_hi:[1,0,1]
	v_pk_fma_f32 v[64:65], v[64:65], v[242:243], v[28:29] op_sel_hi:[1,0,1]
	v_mul_f32_e32 v244, 0xbfb8aa3b, v78
	v_mul_f32_e32 v245, 0xbfb8aa3b, v79
	v_mul_f32_e32 v246, 0xbfb8aa3b, v80
	v_mul_f32_e32 v247, 0xbfb8aa3b, v81
	v_mul_f32_e32 v248, 0xbfb8aa3b, v74
	v_mul_f32_e32 v249, 0xbfb8aa3b, v75
	v_mul_f32_e32 v250, 0xbfb8aa3b, v76
	v_mul_f32_e32 v251, 0xbfb8aa3b, v77
	v_exp_f32_e32 v244, v244
	v_exp_f32_e32 v245, v245
	v_exp_f32_e32 v246, v246
	v_exp_f32_e32 v247, v247
	v_exp_f32_e32 v248, v248
	v_exp_f32_e32 v249, v249
	v_exp_f32_e32 v250, v250
	v_exp_f32_e32 v251, v251
	v_add_f32_e32 v244, 1.0, v244
	v_add_f32_e32 v245, 1.0, v245
	v_add_f32_e32 v246, 1.0, v246
	v_add_f32_e32 v247, 1.0, v247
	v_add_f32_e32 v248, 1.0, v248
	v_add_f32_e32 v249, 1.0, v249
	v_add_f32_e32 v250, 1.0, v250
	v_add_f32_e32 v251, 1.0, v251
	v_rcp_f32_e32 v244, v244
	v_rcp_f32_e32 v245, v245
	v_rcp_f32_e32 v246, v246
	v_rcp_f32_e32 v247, v247
	v_rcp_f32_e32 v248, v248
	v_rcp_f32_e32 v249, v249
	v_rcp_f32_e32 v250, v250
	v_rcp_f32_e32 v251, v251
	v_mul_f32_e32 v244, v78, v244
	v_mul_f32_e32 v245, v79, v245
	v_mul_f32_e32 v246, v80, v246
	v_mul_f32_e32 v247, v81, v247
	v_mul_f32_e32 v248, v74, v248
	v_mul_f32_e32 v249, v75, v249
	v_mul_f32_e32 v250, v76, v250
	v_mul_f32_e32 v251, v77, v251
	v_mul_f32_e32 v244, v70, v244
	v_mul_f32_e32 v245, v71, v245
	v_mul_f32_e32 v246, v72, v246
	v_mul_f32_e32 v247, v73, v247
	v_mul_f32_e32 v248, v62, v248
	v_mul_f32_e32 v249, v63, v249
	v_mul_f32_e32 v250, v64, v250
	v_mul_f32_e32 v251, v65, v251
	v_cvt_pk_bf16_f32 v156, v244, v245
	v_cvt_pk_bf16_f32 v157, v246, v247
	v_cvt_pk_bf16_f32 v158, v248, v249
	v_cvt_pk_bf16_f32 v159, v250, v251
	global_store_dwordx4 v252, v[156:159], s[6:7]
	v_add_u32_e32 v252, 0x16000, v252
	v_fmamk_f32 v242, v238, 0x3a800000, v231
	v_rsq_f32_e32 v242, v242
	s_nop 0
	v_pk_fma_f32 v[66:67], v[66:67], v[242:243], v[54:55] op_sel_hi:[1,0,1]
	v_pk_fma_f32 v[68:69], v[68:69], v[242:243], v[56:57] op_sel_hi:[1,0,1]
	v_pk_fma_f32 v[58:59], v[58:59], v[242:243], v[50:51] op_sel_hi:[1,0,1]
	v_pk_fma_f32 v[60:61], v[60:61], v[242:243], v[52:53] op_sel_hi:[1,0,1]
	v_pk_fma_f32 v[46:47], v[46:47], v[242:243], v[30:31] op_sel_hi:[1,0,1]
	v_pk_fma_f32 v[48:49], v[48:49], v[242:243], v[32:33] op_sel_hi:[1,0,1]
	v_pk_fma_f32 v[38:39], v[38:39], v[242:243], v[26:27] op_sel_hi:[1,0,1]
	v_pk_fma_f32 v[40:41], v[40:41], v[242:243], v[28:29] op_sel_hi:[1,0,1]
	v_mul_f32_e32 v244, 0xbfb8aa3b, v66
	v_mul_f32_e32 v245, 0xbfb8aa3b, v67
	v_mul_f32_e32 v246, 0xbfb8aa3b, v68
	v_mul_f32_e32 v247, 0xbfb8aa3b, v69
	v_mul_f32_e32 v248, 0xbfb8aa3b, v58
	v_mul_f32_e32 v249, 0xbfb8aa3b, v59
	v_mul_f32_e32 v250, 0xbfb8aa3b, v60
	v_mul_f32_e32 v251, 0xbfb8aa3b, v61
	v_exp_f32_e32 v244, v244
	v_exp_f32_e32 v245, v245
	v_exp_f32_e32 v246, v246
	v_exp_f32_e32 v247, v247
	v_exp_f32_e32 v248, v248
	v_exp_f32_e32 v249, v249
	v_exp_f32_e32 v250, v250
	v_exp_f32_e32 v251, v251
	v_add_f32_e32 v244, 1.0, v244
	v_add_f32_e32 v245, 1.0, v245
	v_add_f32_e32 v246, 1.0, v246
	v_add_f32_e32 v247, 1.0, v247
	v_add_f32_e32 v248, 1.0, v248
	v_add_f32_e32 v249, 1.0, v249
	v_add_f32_e32 v250, 1.0, v250
	v_add_f32_e32 v251, 1.0, v251
	v_rcp_f32_e32 v244, v244
	v_rcp_f32_e32 v245, v245
	v_rcp_f32_e32 v246, v246
	v_rcp_f32_e32 v247, v247
	v_rcp_f32_e32 v248, v248
	v_rcp_f32_e32 v249, v249
	v_rcp_f32_e32 v250, v250
	v_rcp_f32_e32 v251, v251
	v_mul_f32_e32 v244, v66, v244
	v_mul_f32_e32 v245, v67, v245
	v_mul_f32_e32 v246, v68, v246
	v_mul_f32_e32 v247, v69, v247
	v_mul_f32_e32 v248, v58, v248
	v_mul_f32_e32 v249, v59, v249
	v_mul_f32_e32 v250, v60, v250
	v_mul_f32_e32 v251, v61, v251
	v_mul_f32_e32 v244, v46, v244
	v_mul_f32_e32 v245, v47, v245
	v_mul_f32_e32 v246, v48, v246
	v_mul_f32_e32 v247, v49, v247
	v_mul_f32_e32 v248, v38, v248
	v_mul_f32_e32 v249, v39, v249
	v_mul_f32_e32 v250, v40, v250
	v_mul_f32_e32 v251, v41, v251
	v_cvt_pk_bf16_f32 v156, v244, v245
	v_cvt_pk_bf16_f32 v157, v246, v247
	v_cvt_pk_bf16_f32 v158, v248, v249
	v_cvt_pk_bf16_f32 v159, v250, v251
	global_store_dwordx4 v252, v[156:159], s[6:7]
	v_add_u32_e32 v252, 0x16000, v252
	v_fmamk_f32 v242, v239, 0x3a800000, v231
	v_rsq_f32_e32 v242, v242
	s_nop 0
	v_pk_fma_f32 v[42:43], v[42:43], v[242:243], v[54:55] op_sel_hi:[1,0,1]
; __device__ __forceinline__ unsigned cvt_pk_bf16(float lo, float hi) { unsigned r; asm volatile("v_cvt_pk_bf16_f32 %0, %1, %2" : "=v"(r) : "v"(lo), "v"(hi)); return r; }
; __device__ __forceinline__ float sigmoidf_(float x) { return 1.0f / (1.0f + __builtin_amdgcn_exp2f(-1.4426950408889634f * x)); }
; #define PG8_BAR __builtin_amdgcn_s_barrier()
;     __device__ __forceinline__ void operator()(const f32x4 (&acc)[2][2][4][2], const Unit& u, int wr, int wc, int fr, int fq) const {
;     ...
;             for (int m = 0; m < 4; ++m) { const size_t row = rowb + ai * HALF + m * 16; const float r = __builtin_amdgcn_rsqf(ssq2[row] * (1.0f / 1024.0f) + RMS_EPS);
;                 f32x4 g0 = acc[ai][0][m][0] * r + bg0, g1 = acc[ai][0][m][1] * r + bg1; const f32x4 u0 = acc[ai][1][m][0] * r + bu0, u1 = acc[ai][1][m][1] * r + bu1;
; #pragma unroll
;                 for (int i = 0; i < 4; ++i) { g0[i] = g0[i] * sigmoidf_(g0[i]) * u0[i]; g1[i] = g1[i] * sigmoidf_(g1[i]) * u1[i]; }
;                 u32x4 w; w.x = cvt_pk_bf16(g0[0], g0[1]); w.y = cvt_pk_bf16(g0[2], g0[3]); w.z = cvt_pk_bf16(g1[0], g1[1]); w.w = cvt_pk_bf16(g1[2], g1[3]);
;                 *(u32x4*)(O + row * 2816 + col0) = w; }
; template <class Epi, class Sched, bool ALIGN_EPI = false, bool SP2 = false>
; __device__ __forceinline__ void gemm_phase(PG8_LAS unsigned char* lds, const Gemm g, const Sched& S, const Epi& E) {
;     ...
;         if (!has_next) break;
; #pragma unroll
;         for (int a = 0; a < 2; ++a)
; #pragma unroll
;             for (int b = 0; b < 2; ++b)
; #pragma unroll
;                 for (int m = 0; m < 4; ++m)
; #pragma unroll
;                     for (int n = 0; n < 2; ++n) acc[a][b][m][n] = (f32x4){0.f, 0.f, 0.f, 0.f};
;         cur = nxt; cA = nA; cB = nB; ++ui;
;         if constexpr (ALIGN_EPI) { if (wr == 1) PG8_BAR; }
	v_pk_fma_f32 v[44:45], v[44:45], v[242:243], v[56:57] op_sel_hi:[1,0,1]
	v_pk_fma_f32 v[34:35], v[34:35], v[242:243], v[50:51] op_sel_hi:[1,0,1]
	v_pk_fma_f32 v[36:37], v[36:37], v[242:243], v[52:53] op_sel_hi:[1,0,1]
	v_pk_fma_f32 v[22:23], v[22:23], v[242:243], v[30:31] op_sel_hi:[1,0,1]
	v_pk_fma_f32 v[24:25], v[24:25], v[242:243], v[32:33] op_sel_hi:[1,0,1]
	v_pk_fma_f32 v[14:15], v[14:15], v[242:243], v[26:27] op_sel_hi:[1,0,1]
	v_pk_fma_f32 v[16:17], v[16:17], v[242:243], v[28:29] op_sel_hi:[1,0,1]
	v_mul_f32_e32 v244, 0xbfb8aa3b, v42
	v_mul_f32_e32 v245, 0xbfb8aa3b, v43
	v_mul_f32_e32 v246, 0xbfb8aa3b, v44
	v_mul_f32_e32 v247, 0xbfb8aa3b, v45
	v_mul_f32_e32 v248, 0xbfb8aa3b, v34
	v_mul_f32_e32 v249, 0xbfb8aa3b, v35
	v_mul_f32_e32 v250, 0xbfb8aa3b, v36
	v_mul_f32_e32 v251, 0xbfb8aa3b, v37
	v_exp_f32_e32 v244, v244
	v_exp_f32_e32 v245, v245
	v_exp_f32_e32 v246, v246
	v_exp_f32_e32 v247, v247
	v_exp_f32_e32 v248, v248
	v_exp_f32_e32 v249, v249
	v_exp_f32_e32 v250, v250
	v_exp_f32_e32 v251, v251
	v_add_f32_e32 v244, 1.0, v244
	v_add_f32_e32 v245, 1.0, v245
	v_add_f32_e32 v246, 1.0, v246
	v_add_f32_e32 v247, 1.0, v247
	v_add_f32_e32 v248, 1.0, v248
	v_add_f32_e32 v249, 1.0, v249
	v_add_f32_e32 v250, 1.0, v250
	v_add_f32_e32 v251, 1.0, v251
	v_rcp_f32_e32 v244, v244
	v_rcp_f32_e32 v245, v245
	v_rcp_f32_e32 v246, v246
	v_rcp_f32_e32 v247, v247
	v_rcp_f32_e32 v248, v248
	v_rcp_f32_e32 v249, v249
	v_rcp_f32_e32 v250, v250
	v_rcp_f32_e32 v251, v251
	v_mul_f32_e32 v244, v42, v244
	v_mul_f32_e32 v245, v43, v245
	v_mul_f32_e32 v246, v44, v246
	v_mul_f32_e32 v247, v45, v247
	v_mul_f32_e32 v248, v34, v248
	v_mul_f32_e32 v249, v35, v249
	v_mul_f32_e32 v250, v36, v250
	v_mul_f32_e32 v251, v37, v251
	v_mul_f32_e32 v244, v22, v244
	v_mul_f32_e32 v245, v23, v245
	v_mul_f32_e32 v246, v24, v246
	v_mul_f32_e32 v247, v25, v247
	v_mul_f32_e32 v248, v14, v248
	v_mul_f32_e32 v249, v15, v249
	v_mul_f32_e32 v250, v16, v250
	v_mul_f32_e32 v251, v17, v251
	v_cvt_pk_bf16_f32 v156, v244, v245
	v_cvt_pk_bf16_f32 v157, v246, v247
	v_cvt_pk_bf16_f32 v158, v248, v249
	v_cvt_pk_bf16_f32 v159, v250, v251
	global_store_dwordx4 v252, v[156:159], s[6:7]
	v_add_u32_e32 v252, 0x16000, v252
	v_fmamk_f32 v242, v240, 0x3a800000, v231
	v_rsq_f32_e32 v242, v242
	s_nop 0
	v_pk_fma_f32 v[18:19], v[18:19], v[242:243], v[54:55] op_sel_hi:[1,0,1]
	v_pk_fma_f32 v[20:21], v[20:21], v[242:243], v[56:57] op_sel_hi:[1,0,1]
	v_pk_fma_f32 v[10:11], v[10:11], v[242:243], v[50:51] op_sel_hi:[1,0,1]
	v_pk_fma_f32 v[12:13], v[12:13], v[242:243], v[52:53] op_sel_hi:[1,0,1]
	v_pk_fma_f32 v[6:7], v[6:7], v[242:243], v[30:31] op_sel_hi:[1,0,1]
	v_pk_fma_f32 v[8:9], v[8:9], v[242:243], v[32:33] op_sel_hi:[1,0,1]
	v_pk_fma_f32 v[2:3], v[2:3], v[242:243], v[26:27] op_sel_hi:[1,0,1]
	v_pk_fma_f32 v[4:5], v[4:5], v[242:243], v[28:29] op_sel_hi:[1,0,1]
	v_mul_f32_e32 v244, 0xbfb8aa3b, v18
	v_mul_f32_e32 v245, 0xbfb8aa3b, v19
	v_mul_f32_e32 v246, 0xbfb8aa3b, v20
	v_mul_f32_e32 v247, 0xbfb8aa3b, v21
	v_mul_f32_e32 v248, 0xbfb8aa3b, v10
	v_mul_f32_e32 v249, 0xbfb8aa3b, v11
	v_mul_f32_e32 v250, 0xbfb8aa3b, v12
	v_mul_f32_e32 v251, 0xbfb8aa3b, v13
	v_exp_f32_e32 v244, v244
	v_exp_f32_e32 v245, v245
	v_exp_f32_e32 v246, v246
	v_exp_f32_e32 v247, v247
	v_exp_f32_e32 v248, v248
	v_exp_f32_e32 v249, v249
	v_exp_f32_e32 v250, v250
	v_exp_f32_e32 v251, v251
	v_add_f32_e32 v244, 1.0, v244
	v_add_f32_e32 v245, 1.0, v245
	v_add_f32_e32 v246, 1.0, v246
	v_add_f32_e32 v247, 1.0, v247
	v_add_f32_e32 v248, 1.0, v248
	v_add_f32_e32 v249, 1.0, v249
	v_add_f32_e32 v250, 1.0, v250
	v_add_f32_e32 v251, 1.0, v251
	v_rcp_f32_e32 v244, v244
	v_rcp_f32_e32 v245, v245
	v_rcp_f32_e32 v246, v246
	v_rcp_f32_e32 v247, v247
	v_rcp_f32_e32 v248, v248
	v_rcp_f32_e32 v249, v249
	v_rcp_f32_e32 v250, v250
	v_rcp_f32_e32 v251, v251
	v_mul_f32_e32 v244, v18, v244
	v_mul_f32_e32 v245, v19, v245
	v_mul_f32_e32 v246, v20, v246
	v_mul_f32_e32 v247, v21, v247
	v_mul_f32_e32 v248, v10, v248
	v_mul_f32_e32 v249, v11, v249
	v_mul_f32_e32 v250, v12, v250
	v_mul_f32_e32 v251, v13, v251
	v_mul_f32_e32 v244, v6, v244
	v_mul_f32_e32 v245, v7, v245
	v_mul_f32_e32 v246, v8, v246
	v_mul_f32_e32 v247, v9, v247
	v_mul_f32_e32 v248, v2, v248
	v_mul_f32_e32 v249, v3, v249
	v_mul_f32_e32 v250, v4, v250
	v_mul_f32_e32 v251, v5, v251
	v_cvt_pk_bf16_f32 v156, v244, v245
	v_cvt_pk_bf16_f32 v157, v246, v247
	v_cvt_pk_bf16_f32 v158, v248, v249
	v_cvt_pk_bf16_f32 v159, v250, v251
	global_store_dwordx4 v252, v[156:159], s[6:7]
	s_mov_b64 s[34:35], -1
	s_andn2_b64 vcc, exec, s[40:41]
	s_cbranch_vccnz .LBB0_26
	s_andn2_b64 vcc, exec, s[2:3]
	s_cbranch_vccnz .LBB0_25
	s_barrier
	s_branch .LBB0_25
